# v77: v61 + s_setprio 1/0 around the two MFMA clusters (S=KQ^T, PV) of the FoX loop
# baseline (speedup 1.0000x reference)
; #define MFMA32(a, b, c) __builtin_amdgcn_mfma_f32_32x32x16_bf16((a), (b), (c), 0, 0, 0)
; DI void fox_attn(const Params& P, int bh, int qb, unsigned char* smem, int tt) {
;     ...
;         {
;             bf16x8 kf[2][4];
; #pragma unroll
;             for (int mt = 0; mt < 2; ++mt)
; #pragma unroll
;                 for (int ks = 0; ks < 4; ++ks) kf[mt][ks] = *(const bf16x8*)(Ks + (mt * 32 + r) * 72 + ks * 16 + h2 * 8);
; #pragma unroll
;             for (int mt = 0; mt < 2; ++mt)
; #pragma unroll
;                 for (int g = 0; g < 4; ++g) ckv[mt][g] = *(const f32x4*)(cks + mt * 32 + 8 * g + 4 * h2);
; #pragma unroll
;             for (int e = 0; e < 16; ++e) { sacc[0][e] = 0.f; sacc[1][e] = 0.f; }
;             __builtin_amdgcn_sched_barrier(0);
; #pragma unroll
;             for (int ks = 0; ks < 4; ++ks) { sacc[0] = MFMA32(kf[0][ks], Qf[ks], sacc[0]); sacc[1] = MFMA32(kf[1][ks], Qf[ks], sacc[1]); }
;         }
;         const bool diag = kt >= ntiles - 2;
;         float mx = -1e30f;
;         {
;             const f32x2v csc = {0.125f * L2E, 0.125f * L2E};
; #pragma unroll
;             for (int mt = 0; mt < 2; ++mt)
; #pragma unroll
;                 for (int g = 0; g < 4; ++g) {
;                     const f32x4 ck4 = ckv[mt][g];
;                     const f32x2v c01 = {ck4[0], ck4[1]}, c23 = {ck4[2], ck4[3]};
;                     const f32x2v a01 = {sacc[mt][4 * g], sacc[mt][4 * g + 1]}, a23 = {sacc[mt][4 * g + 2], sacc[mt][4 * g + 3]};
;                     const f32x2v s01 = a01 * csc - c01, s23 = a23 * csc - c23;
;                     sacc[mt][4 * g] = s01.x; sacc[mt][4 * g + 1] = s01.y; sacc[mt][4 * g + 2] = s23.x; sacc[mt][4 * g + 3] = s23.y;
;                     mx = fmaxf(fmaxf(mx, s01.x), s01.y); mx = fmaxf(fmaxf(mx, s23.x), s23.y);
;                 }
;         }
;         if (diag) {
;             mx = -1e30f;
;             const int qrel = q - kt * 64 - 4 * h2;
; #pragma unroll
;             for (int mt = 0; mt < 2; ++mt)
; #pragma unroll
;                 for (int e = 0; e < 16; ++e) {
;                     const int krel = mt * 32 + (e & 3) + 8 * (e >> 2);
;                     const float sv = (krel > qrel) ? -1e30f : sacc[mt][e];
;                     sacc[mt][e] = sv;
;                     mx = fmaxf(mx, sv);
;                 }
;         }
.LBB0_550:
	s_or_b64 exec, exec, s[36:37]
	s_bitcmp1_b32 s56, 0
	s_cselect_b32 s35, 0x4900, 0
	v_add_u32_e32 v0, s35, v125
	v_lshl_add_u32 v42, v124, 1, v0
	ds_read_b128 v[34:37], v42
	ds_read_b128 v[110:113], v42 offset:32
	ds_read_b128 v[114:117], v42 offset:64
	ds_read_b128 v[132:135], v42 offset:96
	ds_read_b128 v[38:41], v42 offset:4608
	ds_read_b128 v[136:139], v42 offset:4640
	ds_read_b128 v[140:143], v42 offset:4672
	ds_read_b128 v[144:147], v42 offset:4704
	ds_read_b128 v[148:151], v0 offset:18432
	ds_read_b128 v[152:155], v0 offset:18464
	ds_read_b128 v[156:159], v0 offset:18496
	ds_read_b128 v[160:163], v0 offset:18528
	ds_read_b128 v[170:173], v0 offset:18560
	ds_read_b128 v[174:177], v0 offset:18592
	ds_read_b128 v[178:181], v0 offset:18624
	ds_read_b128 v[182:185], v0 offset:18656
	s_setprio 1
	s_waitcnt lgkmcnt(14)
	v_mfma_f32_32x32x16_bf16 v[50:65], v[34:37], v[78:81], 0
	v_cmp_ge_u32_e32 vcc, s56, v122
	s_waitcnt lgkmcnt(11)
	v_mfma_f32_32x32x16_bf16 v[34:49], v[38:41], v[78:81], 0
	v_mfma_f32_32x32x16_bf16 v[50:65], v[110:113], v[66:69], v[50:65]
	v_mfma_f32_32x32x16_bf16 v[50:65], v[114:117], v[70:73], v[50:65]
	s_waitcnt lgkmcnt(10)
	v_mfma_f32_32x32x16_bf16 v[34:49], v[136:139], v[66:69], v[34:49]
	v_mfma_f32_32x32x16_bf16 v[50:65], v[132:135], v[74:77], v[50:65]
	s_waitcnt lgkmcnt(9)
	v_mfma_f32_32x32x16_bf16 v[34:49], v[140:143], v[70:73], v[34:49]
	s_waitcnt lgkmcnt(7)
	s_nop 8
	v_fma_f32 v110, v50, s16, -v148
	v_fma_f32 v111, v51, s16, -v149
	v_fma_f32 v50, v52, s16, -v150
	v_fma_f32 v51, v53, s16, -v151
	v_max3_f32 v52, v110, s17, v111
	v_max3_f32 v52, v52, v50, v51
	s_waitcnt lgkmcnt(6)
	v_pk_fma_f32 v[114:115], v[54:55], s[16:17], v[152:153] op_sel_hi:[1,0,1] neg_lo:[0,0,1] neg_hi:[0,0,1]
	v_pk_fma_f32 v[54:55], v[56:57], s[16:17], v[154:155] op_sel_hi:[1,0,1] neg_lo:[0,0,1] neg_hi:[0,0,1]
	v_max3_f32 v52, v52, v114, v115
	v_mfma_f32_32x32x16_bf16 v[34:49], v[144:147], v[74:77], v[34:49]
	s_setprio 0
	v_max3_f32 v52, v52, v54, v55
	s_waitcnt lgkmcnt(5)
	v_fma_f32 v112, v58, s16, -v156
	v_fma_f32 v113, v59, s16, -v157
	v_fma_f32 v58, v60, s16, -v158
	v_fma_f32 v59, v61, s16, -v159
	v_max3_f32 v52, v52, v112, v113
	v_max3_f32 v52, v52, v58, v59
	s_waitcnt lgkmcnt(4)
	v_pk_fma_f32 v[116:117], v[62:63], s[16:17], v[160:161] op_sel_hi:[1,0,1] neg_lo:[0,0,1] neg_hi:[0,0,1]
	v_pk_fma_f32 v[56:57], v[64:65], s[16:17], v[162:163] op_sel_hi:[1,0,1] neg_lo:[0,0,1] neg_hi:[0,0,1]
	v_max3_f32 v52, v52, v116, v117
	v_max3_f32 v60, v52, v56, v57
	s_waitcnt lgkmcnt(3)
	v_pk_fma_f32 v[62:63], v[34:35], s[16:17], v[170:171] op_sel_hi:[1,0,1] neg_lo:[0,0,1] neg_hi:[0,0,1]
	v_pk_fma_f32 v[52:53], v[36:37], s[16:17], v[172:173] op_sel_hi:[1,0,1] neg_lo:[0,0,1] neg_hi:[0,0,1]
	v_max3_f32 v34, v60, v62, v63
	v_max3_f32 v34, v34, v52, v53
	s_waitcnt lgkmcnt(2)
	v_pk_fma_f32 v[60:61], v[38:39], s[16:17], v[174:175] op_sel_hi:[1,0,1] neg_lo:[0,0,1] neg_hi:[0,0,1]
	v_pk_fma_f32 v[38:39], v[40:41], s[16:17], v[176:177] op_sel_hi:[1,0,1] neg_lo:[0,0,1] neg_hi:[0,0,1]
	v_max3_f32 v34, v34, v60, v61
	v_max3_f32 v34, v34, v38, v39
	s_waitcnt lgkmcnt(1)
	v_pk_fma_f32 v[42:43], v[42:43], s[16:17], v[178:179] op_sel_hi:[1,0,1] neg_lo:[0,0,1] neg_hi:[0,0,1]
	v_pk_fma_f32 v[36:37], v[44:45], s[16:17], v[180:181] op_sel_hi:[1,0,1] neg_lo:[0,0,1] neg_hi:[0,0,1]
	v_max3_f32 v34, v34, v42, v43
	v_max3_f32 v44, v34, v36, v37
	s_waitcnt lgkmcnt(0)
	v_pk_fma_f32 v[40:41], v[46:47], s[16:17], v[182:183] op_sel_hi:[1,0,1] neg_lo:[0,0,1] neg_hi:[0,0,1]
	v_pk_fma_f32 v[34:35], v[48:49], s[16:17], v[184:185] op_sel_hi:[1,0,1] neg_lo:[0,0,1] neg_hi:[0,0,1]
	v_max3_f32 v44, v44, v40, v41
	v_max3_f32 v44, v44, v34, v35
	s_and_saveexec_b64 s[36:37], vcc
	s_cbranch_execz .LBB0_552
	v_cmp_lt_i32_e32 vcc, -1, v127
	s_nop 1
	v_cndmask_b32_e32 v110, v167, v110, vcc
	v_cmp_lt_i32_e32 vcc, 0, v127
	s_nop 1
	v_cndmask_b32_e32 v111, v167, v111, vcc
	v_cmp_lt_i32_e32 vcc, 1, v127
	v_max3_f32 v44, v110, s17, v111
	s_nop 0
	v_cndmask_b32_e32 v50, v167, v50, vcc
	v_cmp_lt_i32_e32 vcc, 2, v127
	s_nop 1
	v_cndmask_b32_e32 v51, v167, v51, vcc
	v_cmp_lt_i32_e32 vcc, 7, v127
	v_max3_f32 v44, v44, v50, v51
	s_nop 0
	v_cndmask_b32_e32 v114, v167, v114, vcc
	v_cmp_lt_i32_e32 vcc, 8, v127
	s_nop 1
	v_cndmask_b32_e32 v115, v167, v115, vcc
	v_cmp_lt_i32_e32 vcc, 9, v127
	v_max3_f32 v44, v44, v114, v115
	s_nop 0
	v_cndmask_b32_e32 v54, v167, v54, vcc
	v_cmp_lt_i32_e32 vcc, 10, v127
	s_nop 1
	v_cndmask_b32_e32 v55, v167, v55, vcc
	v_cmp_lt_i32_e32 vcc, 15, v127
	v_max3_f32 v44, v44, v54, v55
	s_nop 0
	v_cndmask_b32_e32 v112, v167, v112, vcc
	v_cmp_lt_i32_e32 vcc, 16, v127
	s_nop 1
	v_cndmask_b32_e32 v113, v167, v113, vcc
	v_cmp_lt_i32_e32 vcc, 17, v127
	v_max3_f32 v44, v44, v112, v113
	s_nop 0
	v_cndmask_b32_e32 v58, v167, v58, vcc
	v_cmp_lt_i32_e32 vcc, 18, v127
	s_nop 1
	v_cndmask_b32_e32 v59, v167, v59, vcc
	v_cmp_lt_i32_e32 vcc, 23, v127
	v_max3_f32 v44, v44, v58, v59
	s_nop 0
	v_cndmask_b32_e32 v116, v167, v116, vcc
	v_cmp_lt_i32_e32 vcc, 24, v127
	s_nop 1
	v_cndmask_b32_e32 v117, v167, v117, vcc
	v_cmp_lt_i32_e32 vcc, 25, v127
	v_max3_f32 v44, v44, v116, v117
	s_nop 0
	v_cndmask_b32_e32 v56, v167, v56, vcc
	v_cmp_lt_i32_e32 vcc, 26, v127
	s_nop 1
	v_cndmask_b32_e32 v57, v167, v57, vcc
	v_cmp_lt_i32_e32 vcc, 31, v127
	v_max3_f32 v44, v44, v56, v57
	s_nop 0
	v_cndmask_b32_e32 v62, v167, v62, vcc
	v_cmp_lt_i32_e32 vcc, 32, v127
	s_nop 1
	v_cndmask_b32_e32 v63, v167, v63, vcc
	v_cmp_lt_i32_e32 vcc, 33, v127
	v_max3_f32 v44, v44, v62, v63
	s_nop 0
	v_cndmask_b32_e32 v52, v167, v52, vcc
	v_cmp_lt_i32_e32 vcc, 34, v127
	s_nop 1
	v_cndmask_b32_e32 v53, v167, v53, vcc
	v_cmp_lt_i32_e32 vcc, 39, v127
	v_max3_f32 v44, v44, v52, v53
	s_nop 0
	v_cndmask_b32_e32 v60, v167, v60, vcc
	v_cmp_lt_i32_e32 vcc, 40, v127
	s_nop 1
	v_cndmask_b32_e32 v61, v167, v61, vcc
	v_cmp_lt_i32_e32 vcc, 41, v127
	v_max3_f32 v44, v44, v60, v61
	s_nop 0
	v_cndmask_b32_e32 v38, v167, v38, vcc
	v_cmp_lt_i32_e32 vcc, 42, v127
	s_nop 1
	v_cndmask_b32_e32 v39, v167, v39, vcc
	v_cmp_lt_i32_e32 vcc, 47, v127
	v_max3_f32 v44, v44, v38, v39
	s_nop 0
	v_cndmask_b32_e32 v42, v167, v42, vcc
	v_cmp_lt_i32_e32 vcc, 48, v127
	s_nop 1
	v_cndmask_b32_e32 v43, v167, v43, vcc
	v_cmp_lt_i32_e32 vcc, 49, v127
	v_max3_f32 v44, v44, v42, v43
	s_nop 0
	v_cndmask_b32_e32 v36, v167, v36, vcc
	v_cmp_lt_i32_e32 vcc, 50, v127
	s_nop 1
	v_cndmask_b32_e32 v37, v167, v37, vcc
	v_cmp_lt_i32_e32 vcc, 55, v127
	v_max3_f32 v44, v44, v36, v37
	s_nop 0
	v_cndmask_b32_e32 v40, v167, v40, vcc
	v_cmp_lt_i32_e32 vcc, 56, v127
	s_nop 1
	v_cndmask_b32_e32 v41, v167, v41, vcc
	v_cmp_lt_i32_e32 vcc, 57, v127
	v_max3_f32 v44, v44, v40, v41
	s_nop 0
	v_cndmask_b32_e32 v34, v167, v34, vcc
	v_cmp_lt_i32_e32 vcc, 58, v127
	s_nop 1
	v_cndmask_b32_e32 v35, v167, v35, vcc
	v_max3_f32 v44, v44, v34, v35

; DI void fox_attn(const Params& P, int bh, int qb, unsigned char* smem, int tt) {
;     ...
;         {
;             const float sh = cq - m;
;             const f32x2v sh2 = {sh, sh};
;             f32x2v rs2 = {0.f, 0.f};
; #pragma unroll
;             for (int mt = 0; mt < 2; ++mt)
; #pragma unroll
;                 for (int p2 = 0; p2 < 8; ++p2) {
;                     const f32x2v sv = {sacc[mt][2 * p2], sacc[mt][2 * p2 + 1]};
;                     const f32x2v t = sv + sh2;
;                     f32x2v pp; pp.x = __builtin_amdgcn_exp2f(t.x); pp.y = __builtin_amdgcn_exp2f(t.y);
;                     sacc[mt][2 * p2] = pp.x; sacc[mt][2 * p2 + 1] = pp.y;
;                     rs2 = rs2 + pp;
;                 }
;             l += rs2.x + rs2.y;
;         }
;         {
;             u32x4 vw[2][2][2];
; #pragma unroll
;             for (int mt = 0; mt < 2; ++mt)
; #pragma unroll
;                 for (int s = 0; s < 2; ++s)
; #pragma unroll
;                     for (int dt = 0; dt < 2; ++dt) {
;                         const bf16_t* vp = VTs + (dt * 32 + r) * 72 + mt * 32 + 16 * s + 4 * h2;
;                         const u32x2 lo = *(const u32x2*)vp, hi = *(const u32x2*)(vp + 8);
;                         vw[mt][s][dt].x = lo.x; vw[mt][s][dt].y = lo.y; vw[mt][s][dt].z = hi.x; vw[mt][s][dt].w = hi.y;
;                     }
;             u32x4 pw[2][2];
; #pragma unroll
;             for (int mt = 0; mt < 2; ++mt)
; #pragma unroll
;                 for (int s = 0; s < 2; ++s) {
;                     pw[mt][s].x = pack2(sacc[mt][8 * s + 0], sacc[mt][8 * s + 1]); pw[mt][s].y = pack2(sacc[mt][8 * s + 2], sacc[mt][8 * s + 3]);
;                     pw[mt][s].z = pack2(sacc[mt][8 * s + 4], sacc[mt][8 * s + 5]); pw[mt][s].w = pack2(sacc[mt][8 * s + 6], sacc[mt][8 * s + 7]);
;                 }
;             __builtin_amdgcn_sched_barrier(0);
; #pragma unroll
;             for (int mt = 0; mt < 2; ++mt)
; #pragma unroll
;                 for (int s = 0; s < 2; ++s) {
;                     const bf16x8 pf = __builtin_bit_cast(bf16x8, pw[mt][s]);
;                     O[0] = MFMA32(__builtin_bit_cast(bf16x8, vw[mt][s][0]), pf, O[0]);
;                     O[1] = MFMA32(__builtin_bit_cast(bf16x8, vw[mt][s][1]), pf, O[1]);
;                 }
;         }
;         if (more) {
;             unsigned char* bufn = smem + ((kt + 1) & 1) * BUFB;
.LBB0_554:
	v_sub_f32_e32 v132, v121, v128
	v_pk_add_f32 v[44:45], v[110:111], v[132:133] op_sel_hi:[1,0]
	v_lshlrev_b32_e32 v110, 1, v124
	v_add3_u32 v0, v0, v126, v110
	v_add_u32_e32 v129, 0x2000, v0
	v_add_u32_e32 v0, 0x3000, v0
	v_pk_add_f32 v[46:47], v[50:51], v[132:133] op_sel_hi:[1,0]
	v_pk_add_f32 v[48:49], v[114:115], v[132:133] op_sel_hi:[1,0]
	v_pk_add_f32 v[50:51], v[54:55], v[132:133] op_sel_hi:[1,0]
	v_pk_add_f32 v[54:55], v[112:113], v[132:133] op_sel_hi:[1,0]
	v_pk_add_f32 v[58:59], v[58:59], v[132:133] op_sel_hi:[1,0]
	v_pk_add_f32 v[64:65], v[116:117], v[132:133] op_sel_hi:[1,0]
	v_pk_add_f32 v[56:57], v[56:57], v[132:133] op_sel_hi:[1,0]
	v_pk_add_f32 v[62:63], v[62:63], v[132:133] op_sel_hi:[1,0]
	v_pk_add_f32 v[52:53], v[52:53], v[132:133] op_sel_hi:[1,0]
	v_pk_add_f32 v[60:61], v[60:61], v[132:133] op_sel_hi:[1,0]
	v_pk_add_f32 v[38:39], v[38:39], v[132:133] op_sel_hi:[1,0]
	v_pk_add_f32 v[42:43], v[42:43], v[132:133] op_sel_hi:[1,0]
	v_pk_add_f32 v[36:37], v[36:37], v[132:133] op_sel_hi:[1,0]
	v_pk_add_f32 v[40:41], v[40:41], v[132:133] op_sel_hi:[1,0]
	v_pk_add_f32 v[34:35], v[34:35], v[132:133] op_sel_hi:[1,0]
	ds_read2_b64 v[110:113], v129 offset0:128 offset1:130
	ds_read2_b64 v[114:117], v129 offset0:132 offset1:134
	ds_read2_b64 v[132:135], v0 offset0:192 offset1:194
	ds_read2_b64 v[136:139], v0 offset0:196 offset1:198
	ds_read2_b64 v[140:143], v129 offset0:136 offset1:138
	ds_read2_b64 v[144:147], v0 offset0:200 offset1:202
	ds_read2_b64 v[148:151], v129 offset0:140 offset1:142
	ds_read2_b64 v[152:155], v0 offset0:204 offset1:206
	v_exp_f32_e32 v44, v44
	v_exp_f32_e32 v45, v45
	v_exp_f32_e32 v46, v46
	v_exp_f32_e32 v47, v47
	v_exp_f32_e32 v48, v48
	v_exp_f32_e32 v49, v49
	v_exp_f32_e32 v50, v50
	v_exp_f32_e32 v51, v51
	v_exp_f32_e32 v54, v54
	v_exp_f32_e32 v55, v55
	v_exp_f32_e32 v58, v58
	v_exp_f32_e32 v59, v59
	v_exp_f32_e32 v64, v64
	v_exp_f32_e32 v65, v65
	v_exp_f32_e32 v56, v56
	v_exp_f32_e32 v57, v57
	v_exp_f32_e32 v62, v62
	v_exp_f32_e32 v63, v63
	v_exp_f32_e32 v52, v52
	v_exp_f32_e32 v53, v53
	v_exp_f32_e32 v60, v60
	v_exp_f32_e32 v61, v61
	v_exp_f32_e32 v38, v38
	v_exp_f32_e32 v39, v39
	v_exp_f32_e32 v42, v42
	v_exp_f32_e32 v43, v43
	v_exp_f32_e32 v36, v36
	v_exp_f32_e32 v37, v37
	v_exp_f32_e32 v40, v40
	v_exp_f32_e32 v41, v41
	v_exp_f32_e32 v34, v34
	v_exp_f32_e32 v35, v35
	v_cvt_pk_bf16_f32 v156, v44, v45
	v_cvt_pk_bf16_f32 v157, v46, v47
	v_cvt_pk_bf16_f32 v158, v48, v49
	v_cvt_pk_bf16_f32 v159, v50, v51
	v_cvt_pk_bf16_f32 v160, v54, v55
	v_cvt_pk_bf16_f32 v161, v58, v59
	v_cvt_pk_bf16_f32 v162, v64, v65
	v_cvt_pk_bf16_f32 v163, v56, v57
	v_cvt_pk_bf16_f32 v170, v62, v63
	v_cvt_pk_bf16_f32 v171, v52, v53
	v_cvt_pk_bf16_f32 v172, v60, v61
	v_cvt_pk_bf16_f32 v173, v38, v39
	v_cvt_pk_bf16_f32 v174, v42, v43
	v_cvt_pk_bf16_f32 v175, v36, v37
	v_cvt_pk_bf16_f32 v176, v40, v41
	v_cvt_pk_bf16_f32 v177, v34, v35
	s_setprio 1
	s_waitcnt lgkmcnt(7)
	v_mfma_f32_32x32x16_bf16 v[18:33], v[110:113], v[156:159], v[18:33]
	s_waitcnt lgkmcnt(5)
	v_mfma_f32_32x32x16_bf16 v[2:17], v[132:135], v[156:159], v[2:17]
	v_mfma_f32_32x32x16_bf16 v[18:33], v[114:117], v[160:163], v[18:33]
	s_waitcnt lgkmcnt(4)
	v_mfma_f32_32x32x16_bf16 v[2:17], v[136:139], v[160:163], v[2:17]
	s_waitcnt lgkmcnt(3)
	v_mfma_f32_32x32x16_bf16 v[18:33], v[140:143], v[170:173], v[18:33]
	s_waitcnt lgkmcnt(2)
	v_mfma_f32_32x32x16_bf16 v[2:17], v[144:147], v[170:173], v[2:17]
	s_waitcnt lgkmcnt(1)
	v_mfma_f32_32x32x16_bf16 v[18:33], v[148:151], v[174:177], v[18:33]
	s_waitcnt lgkmcnt(0)
	v_mfma_f32_32x32x16_bf16 v[2:17], v[152:155], v[174:177], v[2:17]
	s_setprio 0
	s_and_saveexec_b64 s[36:37], s[2:3]
	s_cbranch_execz .LBB0_545
	s_bitcmp1_b32 s47, 0
	s_cselect_b32 s2, 0x4900, 0
	v_add_u32_e32 v0, s2, v131
	v_add3_u32 v110, v0, v119, v104
	s_waitcnt vmcnt(3)
	ds_write_b128 v110, v[82:85]
	s_waitcnt vmcnt(2)
	ds_write_b128 v110, v[86:89] offset:4608
	s_waitcnt vmcnt(1)
	ds_write_b128 v110, v[90:93] offset:9216
	s_waitcnt vmcnt(0)
	ds_write_b128 v110, v[94:97] offset:13824
	s_and_b64 exec, exec, s[0:1]
	s_cbranch_execz .LBB0_545
	v_mul_f32_e32 v118, 0x3fb8aa3b, v118
	v_lshl_add_u32 v0, v130, 2, v0
	ds_write_b32 v0, v118 offset:18432
	s_branch .LBB0_545
